# attention epilogue: v_permlane32_swap half-wave exchange so each lane stores 16 contiguous bytes (4 dwordx4 instead of 8 dwordx2) on top of the S5 and final-phase edits
# speedup vs baseline: 1.0264x; 1.0077x over previous
.LBB0_648:
	v_mov_b32_e32 v139, v0
	s_waitcnt lgkmcnt(0)
	v_lshl_add_u64 v[216:217], v[138:139], 1, v[156:157]
	s_waitcnt vmcnt(0)
	v_cvt_pk_bf16_f32 v4, v48, v49
	v_cvt_pk_bf16_f32 v5, v50, v51
	v_cvt_pk_bf16_f32 v6, v52, v53
	v_cvt_pk_bf16_f32 v7, v54, v55
	v_cvt_pk_bf16_f32 v8, v56, v57
	v_cvt_pk_bf16_f32 v9, v58, v59
	v_cvt_pk_bf16_f32 v10, v60, v61
	v_cvt_pk_bf16_f32 v11, v62, v63
	v_cvt_pk_bf16_f32 v12, v64, v65
	v_cvt_pk_bf16_f32 v13, v66, v67
	v_cvt_pk_bf16_f32 v14, v68, v69
	v_cvt_pk_bf16_f32 v15, v70, v71
	v_cvt_pk_bf16_f32 v218, v72, v73
	v_cvt_pk_bf16_f32 v219, v74, v75
	v_cvt_pk_bf16_f32 v220, v76, v77
	v_cvt_pk_bf16_f32 v221, v78, v79
	s_nop 1
	v_permlane32_swap_b32_e32 v4, v6
	v_permlane32_swap_b32_e32 v5, v7
	v_permlane32_swap_b32_e32 v8, v10
	v_permlane32_swap_b32_e32 v9, v11
	v_permlane32_swap_b32_e32 v12, v14
	v_permlane32_swap_b32_e32 v13, v15
	v_permlane32_swap_b32_e32 v218, v220
	v_permlane32_swap_b32_e32 v219, v221
	global_store_dwordx4 v[216:217], v[4:7], off
	global_store_dwordx4 v[216:217], v[8:11], off offset:32
	global_store_dwordx4 v[216:217], v[12:15], off offset:64
	global_store_dwordx4 v[216:217], v[218:221], off offset:96
	s_add_i32 s20, s20, s72
	s_cmpk_lt_i32 s20, 0x4000
	s_cbranch_scc0 .LBB0_656
